# v013 + GLA128 segment prefix via exec-masked accumulate (16 v_cndmask removed), the twin of the GLA64 edit
# speedup vs baseline: 1.0085x; 1.0085x over previous
; __device__ __forceinline__ unsigned pk2(float lo, float hi) { const f32x2_t v = {lo, hi}; return __builtin_bit_cast(unsigned, __builtin_convertvector(v, bf16x2_t)); }
; __device__ __forceinline__ f32x2 ex2v(f32x2 x) { f32x2 r; r.x = __builtin_amdgcn_exp2f(x.x); r.y = __builtin_amdgcn_exp2f(x.y); return r; }
; template <int DKH, int DVW>
; __device__ __forceinline__ void gla_chain(const Params& p, int jl, unsigned char* lds, int seq, int h, int e, int dk0, int dv0, bf16_t* OUTB, int ostride, int orow_off) {
;     ...
;             for (int s = 0; s < NSEG; ++s) { const f32x2 sv = *(const f32x2*)(segtot + s * DKH + 2 * dkp); tot += sv; const bool inc = e == 0 ? (s < seg) : (s > seg); off += inc ? sv : (f32x2){0.f, 0.f}; }
;             const f32x2 dec = ex2v(tot);
;             if (seg == 0) *(f32x2*)(decs + 2 * dkp) = dec;
;             f32x2 ke[NP];
; #pragma unroll
;             for (int i = 0; i < NP; ++i) { const f32x2 b = bl[i] + off; const f32x2 eb = ex2v(b), enb = ex2v(-b);
;                 const f32x2 qf = (f32x2){__uint_as_float(qraw[i] << 16), __uint_as_float(qraw[i] & 0xffff0000u)} * QSCALE * eb;
;                 const f32x2 kf = (f32x2){__uint_as_float(kraw[i] << 16), __uint_as_float(kraw[i] & 0xffff0000u)} * enb;
;                 *(unsigned*)(qd + (seg * NP + i) * 272 + dkp * 4) = pk2(qf.x, qf.y);
;                 *(unsigned*)(kd + (seg * NP + i) * 272 + dkp * 4) = pk2(kf.x, kf.y);
;                 ke[i] = kf * dec; }
.LBB0_256:
	s_mov_b64 s[98:99], exec
	v_mov_b32_e32 v236, 0
	v_mov_b32_e32 v237, 0
	s_and_b64 exec, s[98:99], s[42:43]
	v_pk_add_f32 v[236:237], v[236:237], v[116:117]
	s_and_b64 exec, s[98:99], s[44:45]
	v_pk_add_f32 v[236:237], v[236:237], v[100:101]
	s_and_b64 exec, s[98:99], s[46:47]
	v_pk_add_f32 v[236:237], v[236:237], v[94:95]
	s_and_b64 exec, s[98:99], s[48:49]
	v_pk_add_f32 v[236:237], v[236:237], v[96:97]
	s_and_b64 exec, s[98:99], s[50:51]
	v_pk_add_f32 v[236:237], v[236:237], v[90:91]
	s_and_b64 exec, s[98:99], s[52:53]
	v_pk_add_f32 v[236:237], v[236:237], v[92:93]
	s_and_b64 exec, s[98:99], s[54:55]
	v_pk_add_f32 v[236:237], v[236:237], v[86:87]
	s_and_b64 exec, s[98:99], s[56:57]
	v_pk_add_f32 v[236:237], v[236:237], v[88:89]
	s_mov_b64 exec, s[98:99]
	v_mov_b32_e32 v86, v236
	v_mov_b32_e32 v87, v237
	s_waitcnt vmcnt(19)
	v_lshlrev_b32_e32 v92, 16, v182
	v_pk_add_f32 v[88:89], v[128:129], v[86:87]
	v_and_b32_e32 v93, 0xffff0000, v182
	v_exp_f32_e32 v90, v88
	v_exp_f32_e32 v91, v89
	v_exp_f32_e64 v88, -v88
	v_exp_f32_e64 v89, -v89
	v_pk_mul_f32 v[92:93], v[92:93], s[28:29] op_sel_hi:[1,0]
	s_waitcnt vmcnt(17)
	v_lshlrev_b32_e32 v94, 16, v180
	v_pk_mul_f32 v[90:91], v[92:93], v[90:91]
	v_lshlrev_b32_e32 v92, 16, v181
	v_and_b32_e32 v93, 0xffff0000, v181
	v_pk_mul_f32 v[88:89], v[88:89], v[92:93]
	v_cvt_pk_bf16_f32 v0, v90, v91
	v_cvt_pk_bf16_f32 v96, v88, v89
	v_pk_mul_f32 v[90:91], v[98:99], v[88:89]
	v_pk_add_f32 v[88:89], v[114:115], v[86:87]
	v_and_b32_e32 v95, 0xffff0000, v180
	v_exp_f32_e32 v92, v88
	v_exp_f32_e32 v93, v89
	v_exp_f32_e64 v88, -v88
	v_exp_f32_e64 v89, -v89
	v_pk_mul_f32 v[94:95], v[94:95], s[28:29] op_sel_hi:[1,0]
	v_add_u32_e32 v116, s11, v156
	v_pk_mul_f32 v[92:93], v[94:95], v[92:93]
	s_waitcnt vmcnt(16)
	v_lshlrev_b32_e32 v94, 16, v179
	v_and_b32_e32 v95, 0xffff0000, v179
	v_pk_mul_f32 v[88:89], v[88:89], v[94:95]
	v_cvt_pk_bf16_f32 v92, v92, v93
	v_add_u32_e32 v114, 0x3400, v116
	ds_write2_b32 v114, v0, v92 offset1:68
	v_cvt_pk_bf16_f32 v0, v88, v89
	v_pk_mul_f32 v[92:93], v[98:99], v[88:89]
	v_pk_add_f32 v[88:89], v[112:113], v[86:87]
	v_add_u32_e32 v115, 0x7800, v116
	v_exp_f32_e32 v94, v88
	v_exp_f32_e32 v95, v89
	v_exp_f32_e64 v88, -v88
	v_exp_f32_e64 v89, -v89
	ds_write2_b32 v115, v96, v0 offset1:68
	s_waitcnt vmcnt(15)
	v_lshlrev_b32_e32 v96, 16, v178
	v_and_b32_e32 v97, 0xffff0000, v178
	v_pk_mul_f32 v[96:97], v[96:97], s[28:29] op_sel_hi:[1,0]
	s_waitcnt vmcnt(13)
	v_lshlrev_b32_e32 v100, 16, v175
	v_pk_mul_f32 v[94:95], v[96:97], v[94:95]
	v_lshlrev_b32_e32 v96, 16, v177
	v_and_b32_e32 v97, 0xffff0000, v177
	v_pk_mul_f32 v[88:89], v[88:89], v[96:97]
	v_cvt_pk_bf16_f32 v0, v94, v95
	v_cvt_pk_bf16_f32 v112, v88, v89
	v_pk_mul_f32 v[94:95], v[98:99], v[88:89]
	v_pk_add_f32 v[88:89], v[110:111], v[86:87]
	v_and_b32_e32 v101, 0xffff0000, v175
	v_exp_f32_e32 v96, v88
	v_exp_f32_e32 v97, v89
	v_exp_f32_e64 v88, -v88
	v_exp_f32_e64 v89, -v89
	v_pk_mul_f32 v[100:101], v[100:101], s[28:29] op_sel_hi:[1,0]
	v_add_u32_e32 v111, 0x3800, v116
	v_pk_mul_f32 v[96:97], v[100:101], v[96:97]
	s_waitcnt vmcnt(12)
	v_lshlrev_b32_e32 v100, 16, v173
	v_and_b32_e32 v101, 0xffff0000, v173
	v_pk_mul_f32 v[88:89], v[88:89], v[100:101]
	v_cvt_pk_bf16_f32 v96, v96, v97
	ds_write2_b32 v114, v0, v96 offset0:136 offset1:204
	v_cvt_pk_bf16_f32 v0, v88, v89
	v_pk_mul_f32 v[96:97], v[98:99], v[88:89]
	v_pk_add_f32 v[88:89], v[108:109], v[86:87]
	s_waitcnt vmcnt(11)
	v_lshlrev_b32_e32 v108, 16, v176
	v_exp_f32_e32 v100, v88
	v_exp_f32_e32 v101, v89
	v_exp_f32_e64 v88, -v88
	v_exp_f32_e64 v89, -v89
	v_and_b32_e32 v109, 0xffff0000, v176
	v_pk_mul_f32 v[108:109], v[108:109], s[28:29] op_sel_hi:[1,0]
	ds_write2_b32 v115, v112, v0 offset0:136 offset1:204
	v_pk_mul_f32 v[100:101], v[108:109], v[100:101]
	s_waitcnt vmcnt(10)
	v_lshlrev_b32_e32 v108, 16, v174
	v_and_b32_e32 v109, 0xffff0000, v174
	v_pk_mul_f32 v[88:89], v[88:89], v[108:109]
	v_cvt_pk_bf16_f32 v0, v100, v101
	v_cvt_pk_bf16_f32 v110, v88, v89
	v_pk_mul_f32 v[100:101], v[98:99], v[88:89]
	v_pk_add_f32 v[88:89], v[106:107], v[86:87]
	s_waitcnt vmcnt(9)
	v_lshlrev_b32_e32 v108, 16, v172
	v_exp_f32_e32 v106, v88
	v_exp_f32_e32 v107, v89
	v_exp_f32_e64 v88, -v88
	v_exp_f32_e64 v89, -v89
	v_and_b32_e32 v109, 0xffff0000, v172
	v_pk_mul_f32 v[108:109], v[108:109], s[28:29] op_sel_hi:[1,0]
	v_add_u32_e32 v112, 0x7c00, v116
	v_pk_mul_f32 v[106:107], v[108:109], v[106:107]
	s_waitcnt vmcnt(8)
	v_lshlrev_b32_e32 v108, 16, v171
	v_and_b32_e32 v109, 0xffff0000, v171
	v_pk_mul_f32 v[88:89], v[88:89], v[108:109]
	v_cvt_pk_bf16_f32 v106, v106, v107
	ds_write2_b32 v111, v0, v106 offset0:16 offset1:84
	v_cvt_pk_bf16_f32 v0, v88, v89
	v_pk_mul_f32 v[106:107], v[98:99], v[88:89]
	v_pk_add_f32 v[88:89], v[104:105], v[86:87]
	s_waitcnt vmcnt(7)
	v_lshlrev_b32_e32 v108, 16, v170
	v_exp_f32_e32 v104, v88
	v_exp_f32_e32 v105, v89
	v_exp_f32_e64 v88, -v88
	v_exp_f32_e64 v89, -v89
	v_and_b32_e32 v109, 0xffff0000, v170
	v_pk_mul_f32 v[108:109], v[108:109], s[28:29] op_sel_hi:[1,0]
	v_pk_add_f32 v[86:87], v[102:103], v[86:87]
	v_pk_mul_f32 v[104:105], v[108:109], v[104:105]
	s_waitcnt vmcnt(6)
	v_lshlrev_b32_e32 v108, 16, v169
	v_and_b32_e32 v109, 0xffff0000, v169
	v_pk_mul_f32 v[88:89], v[88:89], v[108:109]
	ds_write2_b32 v112, v110, v0 offset0:16 offset1:84
	v_cvt_pk_bf16_f32 v0, v104, v105
	v_cvt_pk_bf16_f32 v108, v88, v89
	v_pk_mul_f32 v[104:105], v[98:99], v[88:89]
	v_exp_f32_e32 v88, v86
	v_exp_f32_e32 v89, v87
	v_exp_f32_e64 v86, -v86
	v_exp_f32_e64 v87, -v87
	s_waitcnt vmcnt(5)
	v_lshlrev_b32_e32 v102, 16, v168
	v_and_b32_e32 v103, 0xffff0000, v168
	v_pk_mul_f32 v[102:103], v[102:103], s[28:29] op_sel_hi:[1,0]
	s_nop 0
	v_pk_mul_f32 v[88:89], v[102:103], v[88:89]
	s_waitcnt vmcnt(4)
; template <int DKH, int DVW>
; __device__ __forceinline__ void gla_chain(const Params& p, int jl, unsigned char* lds, int seq, int h, int e, int dk0, int dv0, bf16_t* OUTB, int ostride, int orow_off) {
;     ...
;             if constexpr (NP == 8) { u32x4 w0, w1; w0.x = pk2(ke[0].x, ke[1].x); w0.y = pk2(ke[2].x, ke[3].x); w0.z = pk2(ke[4].x, ke[5].x); w0.w = pk2(ke[6].x, ke[7].x);
;               w1.x = pk2(ke[0].y, ke[1].y); w1.y = pk2(ke[2].y, ke[3].y); w1.z = pk2(ke[4].y, ke[5].y); w1.w = pk2(ke[6].y, ke[7].y);
;               *(u32x4*)(keT + (2 * dkp) * 144 + seg * 16) = w0; *(u32x4*)(keT + (2 * dkp + 1) * 144 + seg * 16) = w1; }
;             else { u32x2 w0, w1; w0.x = pk2(ke[0].x, ke[1].x); w0.y = pk2(ke[2].x, ke[3].x); w1.x = pk2(ke[0].y, ke[1].y); w1.y = pk2(ke[2].y, ke[3].y);
;               *(u32x2*)(keT + (2 * dkp) * 144 + seg * 8) = w0; *(u32x2*)(keT + (2 * dkp + 1) * 144 + seg * 8) = w1; }
; #pragma unroll
;             for (int jv = 0; jv < NV; ++jv) { const unsigned wd[4] = {vraw[jv].x, vraw[jv].y, vraw[jv].z, vraw[jv].w};
; #pragma unroll
;                 for (int k2 = 0; k2 < 4; ++k2) { const unsigned r = wd[k2], q = (unsigned)__builtin_amdgcn_mov_dpp((int)r, 0xB1, 0xf, 0xf, true);
;                     const bool odd = (lane & 1) != 0;
;                     const unsigned word = odd ? ((q >> 16) | (r & 0xffff0000u)) : ((r & 0xffffu) | (q << 16));
;                     *(unsigned*)(vTw + (jv * 8 + 2 * k2 + (odd ? 1 : 0)) * 144 + (lane >> 1) * 4) = word; } }
;             LDS_BARRIER();
;             { const int st = wave >> 1, ct0 = (wave & 1) * 2;
;               bf16x8 Af[KS], Bf[2][KS];
; #pragma unroll
;               for (int ks = 0; ks < KS; ++ks) { Af[ks] = *(const bf16x8*)(kd + (st * 16 + fr) * 272 + (ks * 32 + fq * 8) * 2);
;                   Bf[0][ks] = *(const bf16x8*)(qd + (ct0 * 16 + fr) * 272 + (ks * 32 + fq * 8) * 2); Bf[1][ks] = *(const bf16x8*)(qd + ((ct0 + 1) * 16 + fr) * 272 + (ks * 32 + fq * 8) * 2); }
;               __builtin_amdgcn_sched_barrier(0);
;               f32x4 a0 = (f32x4){0.f, 0.f, 0.f, 0.f}, a1 = a0;
; #pragma unroll
;               for (int ks = 0; ks < KS; ++ks) { a0 = __builtin_amdgcn_mfma_f32_16x16x32_bf16(Af[ks], Bf[0][ks], a0, 0, 0, 0); a1 = __builtin_amdgcn_mfma_f32_16x16x32_bf16(Af[ks], Bf[1][ks], a1, 0, 0, 0); }
;               const int sb = st * 16 + fq * 4;
; #pragma unroll
	v_lshlrev_b32_e32 v102, 16, v167
	v_and_b32_e32 v103, 0xffff0000, v167
	v_pk_mul_f32 v[86:87], v[86:87], v[102:103]
	v_cvt_pk_bf16_f32 v88, v88, v89
	v_pk_mul_f32 v[98:99], v[98:99], v[86:87]
	ds_write2_b32 v111, v0, v88 offset0:152 offset1:220
	v_cvt_pk_bf16_f32 v0, v86, v87
	v_cvt_pk_bf16_f32 v86, v90, v92
	v_cvt_pk_bf16_f32 v87, v94, v96
	v_cvt_pk_bf16_f32 v88, v100, v106
	v_cvt_pk_bf16_f32 v89, v104, v98
	ds_write2_b32 v112, v108, v0 offset0:152 offset1:220
	v_cvt_pk_bf16_f32 v90, v91, v93
	v_cvt_pk_bf16_f32 v91, v95, v97
	v_cvt_pk_bf16_f32 v92, v101, v107
	v_cvt_pk_bf16_f32 v93, v105, v99
	ds_write_b128 v158, v[86:89] offset:48128
	ds_write_b128 v158, v[90:93] offset:48272
	s_waitcnt vmcnt(0)
	v_mov_b32_dpp v86, v82 quad_perm:[1,0,3,2] row_mask:0xf bank_mask:0xf bound_ctrl:1
	v_perm_b32 v0, v86, v82, v254
	v_mov_b32_dpp v82, v83 quad_perm:[1,0,3,2] row_mask:0xf bank_mask:0xf bound_ctrl:1
	ds_write_b32 v166, v0
	v_perm_b32 v0, v82, v83, v254
	v_mov_b32_dpp v82, v84 quad_perm:[1,0,3,2] row_mask:0xf bank_mask:0xf bound_ctrl:1
	ds_write_b32 v166, v0 offset:288
	v_perm_b32 v0, v82, v84, v254
	v_mov_b32_dpp v82, v85 quad_perm:[1,0,3,2] row_mask:0xf bank_mask:0xf bound_ctrl:1
	ds_write_b32 v166, v0 offset:576
	v_perm_b32 v0, v82, v85, v254
	v_mov_b32_dpp v82, v78 quad_perm:[1,0,3,2] row_mask:0xf bank_mask:0xf bound_ctrl:1
	ds_write_b32 v166, v0 offset:864
	v_perm_b32 v0, v82, v78, v254
	v_mov_b32_dpp v78, v79 quad_perm:[1,0,3,2] row_mask:0xf bank_mask:0xf bound_ctrl:1
	ds_write_b32 v166, v0 offset:1152
	v_perm_b32 v0, v78, v79, v254
	v_mov_b32_dpp v78, v80 quad_perm:[1,0,3,2] row_mask:0xf bank_mask:0xf bound_ctrl:1
	ds_write_b32 v166, v0 offset:1440
	v_perm_b32 v0, v78, v80, v254
	v_mov_b32_dpp v78, v81 quad_perm:[1,0,3,2] row_mask:0xf bank_mask:0xf bound_ctrl:1
	ds_write_b32 v166, v0 offset:1728
	v_perm_b32 v0, v78, v81, v254
	v_mov_b32_dpp v78, v74 quad_perm:[1,0,3,2] row_mask:0xf bank_mask:0xf bound_ctrl:1
	ds_write_b32 v166, v0 offset:2016
	v_perm_b32 v0, v78, v74, v254
	v_mov_b32_dpp v74, v75 quad_perm:[1,0,3,2] row_mask:0xf bank_mask:0xf bound_ctrl:1
	ds_write_b32 v166, v0 offset:2304
	v_perm_b32 v0, v74, v75, v254
	v_mov_b32_dpp v74, v76 quad_perm:[1,0,3,2] row_mask:0xf bank_mask:0xf bound_ctrl:1
	ds_write_b32 v166, v0 offset:2592
	v_perm_b32 v0, v74, v76, v254
	v_mov_b32_dpp v74, v77 quad_perm:[1,0,3,2] row_mask:0xf bank_mask:0xf bound_ctrl:1
	ds_write_b32 v166, v0 offset:2880
	v_perm_b32 v0, v74, v77, v254
	v_mov_b32_dpp v74, v70 quad_perm:[1,0,3,2] row_mask:0xf bank_mask:0xf bound_ctrl:1
	ds_write_b32 v166, v0 offset:3168
	v_perm_b32 v0, v74, v70, v254
	v_mov_b32_dpp v70, v71 quad_perm:[1,0,3,2] row_mask:0xf bank_mask:0xf bound_ctrl:1
	ds_write_b32 v166, v0 offset:3456
	v_perm_b32 v0, v70, v71, v254
	v_mov_b32_dpp v70, v72 quad_perm:[1,0,3,2] row_mask:0xf bank_mask:0xf bound_ctrl:1
	ds_write_b32 v166, v0 offset:3744
	v_perm_b32 v0, v70, v72, v254
	v_mov_b32_dpp v70, v73 quad_perm:[1,0,3,2] row_mask:0xf bank_mask:0xf bound_ctrl:1
	ds_write_b32 v166, v0 offset:4032
	v_perm_b32 v0, v70, v73, v254
	ds_write_b32 v166, v0 offset:4320
	s_waitcnt lgkmcnt(0)
	s_barrier
	ds_read_b128 v[70:73], v159 offset:30720
	ds_read_b128 v[74:77], v159 offset:30784
	ds_read_b128 v[78:81], v160 offset:13312
	ds_read_b128 v[82:85], v160 offset:13376
	ds_read_b128 v[86:89], v160 offset:17664
	ds_read_b128 v[90:93], v160 offset:17728
	ds_read_b128 v[94:97], v159 offset:30848
	ds_read_b128 v[98:101], v159 offset:30912
	ds_read_b128 v[102:105], v160 offset:13440
	ds_read_b128 v[106:109], v160 offset:13504
	ds_read_b128 v[110:113], v160 offset:17792
	ds_read_b128 v[114:117], v160 offset:17856
	s_waitcnt lgkmcnt(9)
	v_mfma_f32_16x16x32_bf16 v[78:81], v[70:73], v[78:81], 0
	v_add_u32_e32 v167, 0x4000, v164
	v_add_u32_e32 v200, 0x5000, v164
	v_add_u32_e32 v201, 0x6000, v164
	s_waitcnt lgkmcnt(7)
	v_mfma_f32_16x16x32_bf16 v[70:73], v[70:73], v[86:89], 0
	v_cvt_pk_bf16_f32 v128, v6, v7
	v_cvt_pk_bf16_f32 v129, v8, v9
	v_cvt_pk_bf16_f32 v130, v14, v15
	v_mfma_f32_16x16x32_bf16 v[78:81], v[74:77], v[82:85], v[78:81]
	v_cvt_pk_bf16_f32 v131, v16, v17
	v_cvt_pk_bf16_f32 v132, v10, v11
	v_cvt_pk_bf16_f32 v133, v12, v13
	s_waitcnt lgkmcnt(6)
	v_mfma_f32_16x16x32_bf16 v[70:73], v[74:77], v[90:93], v[70:73]
	v_cvt_pk_bf16_f32 v134, v18, v19
	v_cvt_pk_bf16_f32 v135, v20, v21
	v_cvt_pk_bf16_f32 v136, v22, v23
	s_waitcnt lgkmcnt(3)
	v_mfma_f32_16x16x32_bf16 v[78:81], v[94:97], v[102:105], v[78:81]
	v_cvt_pk_bf16_f32 v137, v24, v25
	v_cvt_pk_bf16_f32 v138, v30, v31
	v_cvt_pk_bf16_f32 v139, v32, v33
	s_waitcnt lgkmcnt(1)
	v_mfma_f32_16x16x32_bf16 v[70:73], v[94:97], v[110:113], v[70:73]
	v_cvt_pk_bf16_f32 v168, v26, v27
	v_cvt_pk_bf16_f32 v169, v28, v29
	v_cvt_pk_bf16_f32 v170, v34, v35
	v_mfma_f32_16x16x32_bf16 v[78:81], v[98:101], v[106:109], v[78:81]
	v_cvt_pk_bf16_f32 v171, v36, v37
	v_cvt_pk_bf16_f32 v172, v38, v39
	v_cvt_pk_bf16_f32 v173, v40, v41
	s_waitcnt lgkmcnt(0)
	v_mfma_f32_16x16x32_bf16 v[70:73], v[98:101], v[114:117], v[70:73]
	v_cvt_pk_bf16_f32 v174, v46, v47
	s_nop 1
	v_cndmask_b32_e64 v0, 0, v78, s[58:59]
	v_cndmask_b32_e64 v74, 0, v79, s[60:61]
	v_cndmask_b32_e64 v75, 0, v80, s[62:63]
	v_cndmask_b32_e64 v76, 0, v81, s[64:65]
	v_cvt_pk_bf16_f32 v74, v0, v74
	v_cndmask_b32_e64 v0, 0, v70, s[66:67]
	v_cndmask_b32_e64 v70, 0, v71, s[68:69]
	v_cndmask_b32_e64 v71, 0, v72, s[70:71]
	v_cndmask_b32_e64 v72, 0, v73, s[72:73]
	v_cvt_pk_bf16_f32 v75, v75, v76
	v_cvt_pk_bf16_f32 v70, v0, v70
	v_cvt_pk_bf16_f32 v71, v71, v72
	ds_write_b64 v161, v[74:75]
	ds_write_b64 v161, v[70:71] offset:2304
	s_waitcnt lgkmcnt(0)
	s_barrier
; __device__ __forceinline__ unsigned pk2(float lo, float hi) { const f32x2_t v = {lo, hi}; return __builtin_bit_cast(unsigned, __builtin_convertvector(v, bf16x2_t)); }
; template <int DKH, int DVW>
; __device__ __forceinline__ void gla_chain(const Params& p, int jl, unsigned char* lds, int seq, int h, int e, int dk0, int dv0, bf16_t* OUTB, int ostride, int orow_off) {
;     ...
;             bf16x8 vf[DT][2];
; #pragma unroll
;             for (int dt = 0; dt < DT; ++dt)
; #pragma unroll
;                 for (int ks = 0; ks < 2; ++ks) vf[dt][ks] = *(const bf16x8*)(vTw + (dt * 16 + fr) * 144 + (ks * 32 + fq * 8) * 2);
;             f32x4 o[DT][4];
;             { bf16x8 Bs[2][4];
; #pragma unroll
;               for (int ks = 0; ks < 2; ++ks)
; #pragma unroll
;                   for (int ct = 0; ct < 4; ++ct) Bs[ks][ct] = *(const bf16x8*)(sc + (ct * 16 + fr) * 144 + (ks * 32 + fq * 8) * 2);
;               bf16x8 Sbf[KS][DT];
; #pragma unroll
;               for (int ks = 0; ks < KS; ++ks)
; #pragma unroll
;                   for (int dt = 0; dt < DT; ++dt) { const f32x4 x0 = Sacc[2 * ks][dt], x1 = Sacc[2 * ks + 1][dt];
;                       const u32x4 w = (u32x4){pk2(x0[0], x0[1]), pk2(x0[2], x0[3]), pk2(x1[0], x1[1]), pk2(x1[2], x1[3])}; Sbf[ks][dt] = __builtin_bit_cast(bf16x8, w); }
;               u32x4 Bq[2][4];
;     ...
;               GLA_LDQ(0, 0);
;               __builtin_amdgcn_sched_barrier(0);
; #pragma unroll
;               for (int ct = 0; ct < 4; ++ct)
; #pragma unroll
;                   for (int dt = 0; dt < DT; ++dt) o[dt][ct] = __builtin_amdgcn_mfma_f32_16x16x32_bf16(vf[dt][0], Bs[0][ct], (f32x4){0.f, 0.f, 0.f, 0.f}, 0, 0, 0);
; #pragma unroll
;               for (int ct = 0; ct < 4; ++ct)
; #pragma unroll
;                   for (int dt = 0; dt < DT; ++dt) o[dt][ct] = __builtin_amdgcn_mfma_f32_16x16x32_bf16(vf[dt][1], Bs[1][ct], o[dt][ct], 0, 0, 0);
; #pragma unroll
;               for (int ks = 0; ks < KS; ++ks) {
;                   if (ks < KS - 1) GLA_LDQ((ks + 1) & 1, ks + 1);
;                   __builtin_amdgcn_sched_barrier(0);
; #pragma unroll
;                   for (int ct = 0; ct < 4; ++ct) { const bf16x8 B = __builtin_bit_cast(bf16x8, Bq[ks & 1][ct]);
; #pragma unroll
;                       for (int dt = 0; dt < DT; ++dt) o[dt][ct] = __builtin_amdgcn_mfma_f32_16x16x32_bf16(Sbf[ks][dt], B, o[dt][ct], 0, 0, 0); }
	ds_read_b128 v[82:85], v162
	ds_read_b128 v[70:73], v162 offset:64
	ds_read_b128 v[78:81], v162 offset:2304
	ds_read_b128 v[74:77], v162 offset:2368
	ds_read_b128 v[86:89], v163
	ds_read_b128 v[90:93], v163 offset:64
	ds_read_b128 v[94:97], v163 offset:2304
	ds_read_b128 v[98:101], v163 offset:2368
	ds_read_b128 v[102:105], v163 offset:4608
	ds_read_b128 v[106:109], v163 offset:4672
	ds_read_b128 v[110:113], v163 offset:6912
	ds_read_b128 v[114:117], v163 offset:6976
	v_add_u32_e32 v0, 0x3000, v164
	ds_read2_b64 v[184:187], v0 offset0:128 offset1:132
	ds_read2_b64 v[188:191], v167 offset0:160 offset1:164
	ds_read2_b64 v[192:195], v200 offset0:192 offset1:196
	ds_read2_b64 v[196:199], v201 offset0:224 offset1:228
	v_cvt_pk_bf16_f32 v175, v48, v49
	v_cvt_pk_bf16_f32 v176, v42, v43
	v_cvt_pk_bf16_f32 v177, v44, v45
	v_cvt_pk_bf16_f32 v178, v50, v51
	v_cvt_pk_bf16_f32 v179, v52, v53
	v_cvt_pk_bf16_f32 v180, v54, v55
	v_cvt_pk_bf16_f32 v181, v56, v57
	v_cvt_pk_bf16_f32 v182, v62, v63
	v_cvt_pk_bf16_f32 v183, v64, v65
	v_cvt_pk_bf16_f32 v214, v58, v59
	v_cvt_pk_bf16_f32 v215, v60, v61
	v_cvt_pk_bf16_f32 v216, v66, v67
	v_cvt_pk_bf16_f32 v217, v68, v69
	s_waitcnt lgkmcnt(11)
	v_mfma_f32_16x16x32_bf16 v[218:221], v[82:85], v[86:89], 0
	v_mfma_f32_16x16x32_bf16 v[86:89], v[78:81], v[86:89], 0
	s_waitcnt lgkmcnt(9)
	v_mfma_f32_16x16x32_bf16 v[222:225], v[82:85], v[94:97], 0
	v_mfma_f32_16x16x32_bf16 v[94:97], v[78:81], v[94:97], 0
	s_waitcnt lgkmcnt(7)
	v_mfma_f32_16x16x32_bf16 v[226:229], v[82:85], v[102:105], 0
	v_mfma_f32_16x16x32_bf16 v[102:105], v[78:81], v[102:105], 0
	s_waitcnt lgkmcnt(5)
	v_mfma_f32_16x16x32_bf16 v[230:233], v[82:85], v[110:113], 0
	v_mfma_f32_16x16x32_bf16 v[110:113], v[78:81], v[110:113], 0
	v_mfma_f32_16x16x32_bf16 v[218:221], v[70:73], v[90:93], v[218:221]
	v_mfma_f32_16x16x32_bf16 v[86:89], v[74:77], v[90:93], v[86:89]
	v_mfma_f32_16x16x32_bf16 v[90:93], v[70:73], v[98:101], v[222:225]
	v_mfma_f32_16x16x32_bf16 v[94:97], v[74:77], v[98:101], v[94:97]
	v_mfma_f32_16x16x32_bf16 v[98:101], v[70:73], v[106:109], v[226:229]
	v_mfma_f32_16x16x32_bf16 v[102:105], v[74:77], v[106:109], v[102:105]
	s_waitcnt lgkmcnt(4)
	v_mfma_f32_16x16x32_bf16 v[106:109], v[70:73], v[114:117], v[230:233]
	v_mfma_f32_16x16x32_bf16 v[110:113], v[74:77], v[114:117], v[110:113]
	ds_read2_b64 v[114:117], v0 offset0:136 offset1:140
	ds_read2_b64 v[222:225], v167 offset0:168 offset1:172
	ds_read2_b64 v[226:229], v200 offset0:200 offset1:204
	ds_read2_b64 v[230:233], v201 offset0:232 offset1:236
	s_waitcnt lgkmcnt(7)
	v_mfma_f32_16x16x32_bf16 v[218:221], v[128:131], v[184:187], v[218:221]
	v_mfma_f32_16x16x32_bf16 v[86:89], v[132:135], v[184:187], v[86:89]
	s_waitcnt lgkmcnt(6)
	v_mfma_f32_16x16x32_bf16 v[90:93], v[128:131], v[188:191], v[90:93]
	v_mfma_f32_16x16x32_bf16 v[94:97], v[132:135], v[188:191], v[94:97]
	s_waitcnt lgkmcnt(5)
	v_mfma_f32_16x16x32_bf16 v[98:101], v[128:131], v[192:195], v[98:101]
	v_mfma_f32_16x16x32_bf16 v[102:105], v[132:135], v[192:195], v[102:105]
	s_waitcnt lgkmcnt(4)
	v_mfma_f32_16x16x32_bf16 v[106:109], v[128:131], v[196:199], v[106:109]
	v_mfma_f32_16x16x32_bf16 v[110:113], v[132:135], v[196:199], v[110:113]
	ds_read2_b64 v[128:131], v0 offset0:144 offset1:148
	ds_read2_b64 v[132:135], v167 offset0:176 offset1:180
	ds_read2_b64 v[184:187], v200 offset0:208 offset1:212
	ds_read2_b64 v[188:191], v201 offset0:240 offset1:244
	s_waitcnt lgkmcnt(7)
	v_mfma_f32_16x16x32_bf16 v[192:195], v[136:139], v[114:117], v[218:221]
	v_mfma_f32_16x16x32_bf16 v[86:89], v[168:171], v[114:117], v[86:89]
	s_waitcnt lgkmcnt(6)
	v_mfma_f32_16x16x32_bf16 v[90:93], v[136:139], v[222:225], v[90:93]
	v_mfma_f32_16x16x32_bf16 v[94:97], v[168:171], v[222:225], v[94:97]
	s_waitcnt lgkmcnt(5)
	v_mfma_f32_16x16x32_bf16 v[98:101], v[136:139], v[226:229], v[98:101]
	v_mfma_f32_16x16x32_bf16 v[102:105], v[168:171], v[226:229], v[102:105]
	s_waitcnt lgkmcnt(4)
	v_mfma_f32_16x16x32_bf16 v[106:109], v[136:139], v[230:233], v[106:109]
	v_mfma_f32_16x16x32_bf16 v[110:113], v[168:171], v[230:233], v[110:113]
	ds_read2_b64 v[114:117], v0 offset0:152 offset1:156
	ds_read2_b64 v[136:139], v167 offset0:184 offset1:188
	ds_read2_b64 v[168:171], v200 offset0:216 offset1:220
	ds_read2_b64 v[196:199], v201 offset0:248 offset1:252
	s_waitcnt lgkmcnt(7)
	v_mfma_f32_16x16x32_bf16 v[192:195], v[172:175], v[128:131], v[192:195]
	v_mfma_f32_16x16x32_bf16 v[86:89], v[176:179], v[128:131], v[86:89]
	s_waitcnt lgkmcnt(6)
	v_mfma_f32_16x16x32_bf16 v[90:93], v[172:175], v[132:135], v[90:93]
	v_mfma_f32_16x16x32_bf16 v[94:97], v[176:179], v[132:135], v[94:97]
	s_waitcnt lgkmcnt(5)
	v_mfma_f32_16x16x32_bf16 v[98:101], v[172:175], v[184:187], v[98:101]
	v_mfma_f32_16x16x32_bf16 v[102:105], v[176:179], v[184:187], v[102:105]
	s_waitcnt lgkmcnt(4)
	v_mfma_f32_16x16x32_bf16 v[106:109], v[172:175], v[188:191], v[106:109]
	v_mfma_f32_16x16x32_bf16 v[110:113], v[176:179], v[188:191], v[110:113]
	s_waitcnt lgkmcnt(3)
	v_mfma_f32_16x16x32_bf16 v[128:131], v[180:183], v[114:117], v[192:195]
	v_mfma_f32_16x16x32_bf16 v[86:89], v[214:217], v[114:117], v[86:89]
	s_waitcnt lgkmcnt(2)
	v_mfma_f32_16x16x32_bf16 v[90:93], v[180:183], v[136:139], v[90:93]
	v_mfma_f32_16x16x32_bf16 v[94:97], v[214:217], v[136:139], v[94:97]
	s_waitcnt lgkmcnt(1)
	v_mfma_f32_16x16x32_bf16 v[98:101], v[180:183], v[168:171], v[98:101]
	v_mfma_f32_16x16x32_bf16 v[102:105], v[214:217], v[168:171], v[102:105]
	s_waitcnt lgkmcnt(0)
; __device__ __forceinline__ unsigned pk2(float lo, float hi) { const f32x2_t v = {lo, hi}; return __builtin_bit_cast(unsigned, __builtin_convertvector(v, bf16x2_t)); }
; #define GLA_LDK(buf, g_) do { _Pragma("unroll") for (int d2 = 0; d2 < 2; ++d2) { dcv[buf][d2] = *(const f32x4*)(decs + ((g_) * 2 + d2) * 16 + fq * 4); \
;                   _Pragma("unroll") for (int ks = 0; ks < 2; ++ks) Ak[buf][d2][ks] = *(const bf16x8*)(keT + (((g_) * 2 + d2) * 16 + fr) * 144 + (ks * 32 + fq * 8) * 2); } } while (0)
; template <int DKH, int DVW>
; __device__ __forceinline__ void gla_chain(const Params& p, int jl, unsigned char* lds, int seq, int h, int e, int dk0, int dv0, bf16_t* OUTB, int ostride, int orow_off) {
;     ...
; #pragma unroll
;             for (int ct = 0; ct < 4; ++ct)
; #pragma unroll
;                 for (int dt = 0; dt < DT; ++dt) { u32x2 w; w.x = pk2(o[dt][ct][0], o[dt][ct][1]); w.y = pk2(o[dt][ct][2], o[dt][ct][3]);
;                     *(u32x2*)(OUTB + (size_t)(tokc0 - orow_off + ct * 16 + fr) * ostride + h * 256 + dv0 + wave * DVW + dt * 16 + fq * 4) = w; }
;             { bf16x8 Ak[2][2][2]; f32x4 dcv[2][2];
;     ...
;               GLA_LDK(0, 0);
; #pragma unroll
;               for (int g = 0; g < DKT / 2; ++g) {
;                   if (g < DKT / 2 - 1) GLA_LDK((g + 1) & 1, g + 1);
;                   __builtin_amdgcn_sched_barrier(0);
; #pragma unroll
;                   for (int d2 = 0; d2 < 2; ++d2) { const int dkt = g * 2 + d2;
; #pragma unroll
;                       for (int dt = 0; dt < DT; ++dt) Sacc[dkt][dt] *= dcv[g & 1][d2];
; #pragma unroll
;                       for (int ks = 0; ks < 2; ++ks)
; #pragma unroll
;                           for (int dt = 0; dt < DT; ++dt) Sacc[dkt][dt] = __builtin_amdgcn_mfma_f32_16x16x32_bf16(Ak[g & 1][d2][ks], vf[dt][ks], Sacc[dkt][dt], 0, 0, 0); }
;                   __builtin_amdgcn_sched_barrier(0);
;               }
;     ...
;             }
;             if (tid < 256 && n + 1 < nch) *(f32x4*)(g1nxt + gc * 16 + gr4 * 4) = g1n;
	v_mfma_f32_16x16x32_bf16 v[106:109], v[180:183], v[196:199], v[106:109]
	v_mfma_f32_16x16x32_bf16 v[110:113], v[214:217], v[196:199], v[110:113]
	v_or_b32_e32 v0, s82, v141
	v_lshlrev_b32_e32 v0, 10, v0
	v_lshl_add_u64 v[114:115], v[0:1], 1, v[126:127]
	v_cvt_pk_bf16_f32 v86, v86, v87
	v_cvt_pk_bf16_f32 v87, v88, v89
	global_store_dwordx2 v[114:115], v[86:87], off offset:32
	v_ashrrev_i32_e32 v87, 31, v0
	v_mov_b32_e32 v86, v0
	v_lshl_add_u64 v[86:87], v[86:87], 1, v[126:127]
	s_mov_b32 s2, 0x8000
	v_cvt_pk_bf16_f32 v88, v90, v91
	v_add_co_u32_e32 v90, vcc, s2, v86
	v_cvt_pk_bf16_f32 v89, v92, v93
	s_nop 0
	v_addc_co_u32_e32 v91, vcc, 0, v87, vcc
	global_store_dwordx2 v[90:91], v[88:89], off
	v_cvt_pk_bf16_f32 v88, v94, v95
	v_cvt_pk_bf16_f32 v89, v96, v97
	s_mov_b32 s2, 0x10000
	global_store_dwordx2 v[90:91], v[88:89], off offset:32
	v_add_co_u32_e32 v90, vcc, s2, v86
	v_cvt_pk_bf16_f32 v88, v98, v99
	v_cvt_pk_bf16_f32 v89, v100, v101
	v_addc_co_u32_e32 v91, vcc, 0, v87, vcc
	s_mov_b32 s2, 0x18000
	global_store_dwordx2 v[90:91], v[88:89], off
	v_cvt_pk_bf16_f32 v88, v102, v103
	v_cvt_pk_bf16_f32 v89, v104, v105
	v_add_co_u32_e32 v86, vcc, s2, v86
	global_store_dwordx2 v[90:91], v[88:89], off offset:32
	v_cvt_pk_bf16_f32 v88, v106, v107
	v_cvt_pk_bf16_f32 v89, v108, v109
	v_addc_co_u32_e32 v87, vcc, 0, v87, vcc
	v_cvt_pk_bf16_f32 v116, v128, v129
	v_cvt_pk_bf16_f32 v117, v130, v131
	global_store_dwordx2 v[86:87], v[88:89], off
	v_cvt_pk_bf16_f32 v88, v110, v111
	v_cvt_pk_bf16_f32 v89, v112, v113
	global_store_dwordx2 v[114:115], v[116:117], off
	global_store_dwordx2 v[86:87], v[88:89], off offset:32
	v_add_u32_e32 v0, v157, v124
	ds_read_b128 v[86:89], v0 offset:12288
	ds_read_b128 v[90:93], v165 offset:48128
	ds_read_b128 v[94:97], v165 offset:48192
	ds_read_b128 v[98:101], v0 offset:12352
	ds_read_b128 v[102:105], v165 offset:50432
	ds_read_b128 v[106:109], v165 offset:50496
	ds_read_b128 v[110:113], v0 offset:12416
	ds_read_b128 v[114:117], v165 offset:52736
	ds_read_b128 v[128:131], v165 offset:52800
	ds_read_b128 v[132:135], v0 offset:12480
	ds_read_b128 v[136:139], v165 offset:55040
	ds_read_b128 v[168:171], v165 offset:55104
	s_waitcnt lgkmcnt(11)
	v_pk_mul_f32 v[6:7], v[6:7], v[86:87]
	v_pk_mul_f32 v[8:9], v[8:9], v[88:89]
	v_pk_mul_f32 v[10:11], v[10:11], v[86:87]
	v_pk_mul_f32 v[12:13], v[12:13], v[88:89]
	s_waitcnt lgkmcnt(8)
	v_pk_mul_f32 v[14:15], v[14:15], v[98:99]
	v_pk_mul_f32 v[16:17], v[16:17], v[100:101]
	v_pk_mul_f32 v[18:19], v[18:19], v[98:99]
	v_pk_mul_f32 v[20:21], v[20:21], v[100:101]
	v_mfma_f32_16x16x32_bf16 v[6:9], v[90:93], v[82:85], v[6:9]
	v_mfma_f32_16x16x32_bf16 v[10:13], v[90:93], v[78:81], v[10:13]
	s_waitcnt lgkmcnt(7)
	v_mfma_f32_16x16x32_bf16 v[14:17], v[102:105], v[82:85], v[14:17]
	v_mfma_f32_16x16x32_bf16 v[18:21], v[102:105], v[78:81], v[18:21]
	v_mfma_f32_16x16x32_bf16 v[6:9], v[94:97], v[70:73], v[6:9]
	v_mfma_f32_16x16x32_bf16 v[10:13], v[94:97], v[74:77], v[10:13]
	s_waitcnt lgkmcnt(6)
	v_mfma_f32_16x16x32_bf16 v[14:17], v[106:109], v[70:73], v[14:17]
	v_mfma_f32_16x16x32_bf16 v[18:21], v[106:109], v[74:77], v[18:21]
	ds_read_b128 v[86:89], v165 offset:57344
	ds_read_b128 v[90:93], v165 offset:57408
	ds_read_b128 v[94:97], v0 offset:12544
	ds_read_b128 v[98:101], v0 offset:12608
	ds_read_b128 v[102:105], v165 offset:59648
	ds_read_b128 v[106:109], v165 offset:59712
	s_waitcnt lgkmcnt(11)
	v_pk_mul_f32 v[22:23], v[22:23], v[110:111]
	v_pk_mul_f32 v[24:25], v[24:25], v[112:113]
	v_pk_mul_f32 v[26:27], v[26:27], v[110:111]
	v_pk_mul_f32 v[28:29], v[28:29], v[112:113]
	s_waitcnt lgkmcnt(8)
	v_pk_mul_f32 v[30:31], v[30:31], v[132:133]
	v_pk_mul_f32 v[32:33], v[32:33], v[134:135]
	v_pk_mul_f32 v[34:35], v[34:35], v[132:133]
	v_pk_mul_f32 v[36:37], v[36:37], v[134:135]
	v_mfma_f32_16x16x32_bf16 v[22:25], v[114:117], v[82:85], v[22:25]
	v_mfma_f32_16x16x32_bf16 v[26:29], v[114:117], v[78:81], v[26:29]
	s_waitcnt lgkmcnt(7)
	v_mfma_f32_16x16x32_bf16 v[30:33], v[136:139], v[82:85], v[30:33]
	v_mfma_f32_16x16x32_bf16 v[34:37], v[136:139], v[78:81], v[34:37]
	v_mfma_f32_16x16x32_bf16 v[22:25], v[128:131], v[70:73], v[22:25]
	v_mfma_f32_16x16x32_bf16 v[26:29], v[128:131], v[74:77], v[26:29]
	s_waitcnt lgkmcnt(6)
	v_mfma_f32_16x16x32_bf16 v[30:33], v[168:171], v[70:73], v[30:33]
	v_mfma_f32_16x16x32_bf16 v[34:37], v[168:171], v[74:77], v[34:37]
	ds_read_b128 v[110:113], v165 offset:61952
	ds_read_b128 v[114:117], v165 offset:62016
	ds_read_b128 v[128:131], v0 offset:12672
	ds_read_b128 v[132:135], v0 offset:12736
	ds_read_b128 v[136:139], v165 offset:64256
	ds_read_b128 v[168:171], v165 offset:64320
	s_waitcnt lgkmcnt(9)
	v_pk_mul_f32 v[38:39], v[38:39], v[94:95]
	v_pk_mul_f32 v[40:41], v[40:41], v[96:97]
	v_pk_mul_f32 v[42:43], v[42:43], v[94:95]
	v_pk_mul_f32 v[44:45], v[44:45], v[96:97]
	s_waitcnt lgkmcnt(8)
	v_pk_mul_f32 v[46:47], v[46:47], v[98:99]
	v_pk_mul_f32 v[48:49], v[48:49], v[100:101]
	v_pk_mul_f32 v[50:51], v[50:51], v[98:99]
	v_pk_mul_f32 v[52:53], v[52:53], v[100:101]
	v_mfma_f32_16x16x32_bf16 v[38:41], v[86:89], v[82:85], v[38:41]
	v_mfma_f32_16x16x32_bf16 v[42:45], v[86:89], v[78:81], v[42:45]
	s_waitcnt lgkmcnt(7)
	v_mfma_f32_16x16x32_bf16 v[46:49], v[102:105], v[82:85], v[46:49]
	v_mfma_f32_16x16x32_bf16 v[50:53], v[102:105], v[78:81], v[50:53]
	v_mfma_f32_16x16x32_bf16 v[38:41], v[90:93], v[70:73], v[38:41]
	v_mfma_f32_16x16x32_bf16 v[42:45], v[90:93], v[74:77], v[42:45]
	s_waitcnt lgkmcnt(6)
	v_mfma_f32_16x16x32_bf16 v[46:49], v[106:109], v[70:73], v[46:49]
	v_mfma_f32_16x16x32_bf16 v[50:53], v[106:109], v[74:77], v[50:53]
	s_waitcnt lgkmcnt(3)
	v_pk_mul_f32 v[54:55], v[54:55], v[128:129]
	v_pk_mul_f32 v[56:57], v[56:57], v[130:131]
	v_pk_mul_f32 v[58:59], v[58:59], v[128:129]
	v_pk_mul_f32 v[60:61], v[60:61], v[130:131]
	s_waitcnt lgkmcnt(2)
	v_pk_mul_f32 v[62:63], v[62:63], v[132:133]
	v_pk_mul_f32 v[64:65], v[64:65], v[134:135]
	v_pk_mul_f32 v[66:67], v[66:67], v[132:133]
	v_pk_mul_f32 v[68:69], v[68:69], v[134:135]
	v_mfma_f32_16x16x32_bf16 v[54:57], v[110:113], v[82:85], v[54:57]
	v_mfma_f32_16x16x32_bf16 v[58:61], v[110:113], v[78:81], v[58:61]
	s_waitcnt lgkmcnt(1)
	v_mfma_f32_16x16x32_bf16 v[62:65], v[136:139], v[82:85], v[62:65]
	v_mfma_f32_16x16x32_bf16 v[66:69], v[136:139], v[78:81], v[66:69]
	v_mfma_f32_16x16x32_bf16 v[54:57], v[114:117], v[70:73], v[54:57]
	v_mfma_f32_16x16x32_bf16 v[58:61], v[114:117], v[74:77], v[58:61]
	s_waitcnt lgkmcnt(0)
	v_mfma_f32_16x16x32_bf16 v[62:65], v[168:171], v[70:73], v[62:65]
	v_mfma_f32_16x16x32_bf16 v[66:69], v[168:171], v[74:77], v[66:69]
	s_and_saveexec_b64 s[2:3], s[80:81]
	s_cbranch_execz .LBB0_246
	s_and_b32 s5, s75, 0x400
	v_lshl_add_u32 v0, s5, 2, v125
	ds_write_b128 v0, v[2:5]
	s_branch .LBB0_246
